# v41 + mLSTM stage A: the four serialized K-tile loads (load, vmcnt(0), 8 ds_writes each) issued together up front with exact counted waits
# speedup vs baseline: 1.0015x; 1.0015x over previous
; #define LAS __attribute__((address_space(3)))
; __device__ __forceinline__ unsigned f2bf(float f) { unsigned u = __float_as_uint(f); return (u + 0x7fffu + ((u >> 16) & 1u)) >> 16; }
; __device__ __forceinline__ float bflo(unsigned w) { return __uint_as_float(w << 16); }
; __device__ __forceinline__ float bfhi(unsigned w) { return __uint_as_float(w & 0xffff0000u); }
; __device__ __forceinline__ void mlstm_stage_a(LAS unsigned char* lds, const bf16_t* QKO, const bf16_t* KVT, const float* G, const float* gbias, bf16_t* DC, float* DN, float* SC,
;                                               int bid, int nblk, int tid) {
;     ...
;         __syncthreads();
; #pragma unroll
;         for (int i = 0; i < 4; ++i) { const int q = tid + 512 * i, sidx = q & 63, d8 = q >> 6;
;             const u32x4 kv = *(const u32x4*)(QKO + (size_t)(t0 + sidx) * 4096 + 1024 + h * 256 + d8 * 8);
;             const float wk = sWk[sidx];
;             LAS unsigned short* dst = (LAS unsigned short*)(sKS + (d8 * 8) * 144 + sidx * 2);
;             dst[0 * 72] = (unsigned short)f2bf(bflo(kv.x) * wk); dst[1 * 72] = (unsigned short)f2bf(bfhi(kv.x) * wk);
;             dst[2 * 72] = (unsigned short)f2bf(bflo(kv.y) * wk); dst[3 * 72] = (unsigned short)f2bf(bfhi(kv.y) * wk);
;             dst[4 * 72] = (unsigned short)f2bf(bflo(kv.z) * wk); dst[5 * 72] = (unsigned short)f2bf(bfhi(kv.z) * wk);
;             dst[6 * 72] = (unsigned short)f2bf(bflo(kv.w) * wk); dst[7 * 72] = (unsigned short)f2bf(bfhi(kv.w) * wk); }
;         __syncthreads();
.LBB0_540:
	v_lshlrev_b64 v[0:1], 13, v[0:1]
	v_lshl_add_u64 v[0:1], s[66:67], 0, v[0:1]
	s_lshl_b32 s0, s5, 9
	v_lshl_add_u64 v[0:1], v[0:1], 0, s[0:1]
	v_lshl_add_u64 v[2:3], v[166:167], 1, v[0:1]
	s_waitcnt lgkmcnt(0)
	s_barrier
	global_load_dwordx4 v[208:211], v[2:3], off offset:2048
	v_lshl_add_u64 v[228:229], v[172:173], 1, v[0:1]
	global_load_dwordx4 v[220:223], v[228:229], off offset:2048
	v_lshl_add_u64 v[224:225], v[168:169], 1, v[0:1]
	global_load_dwordx4 v[212:215], v[224:225], off offset:2048
	v_lshl_add_u64 v[226:227], v[170:171], 1, v[0:1]
	global_load_dwordx4 v[216:219], v[226:227], off offset:2048
	ds_read_b32 v4, v183
	s_waitcnt vmcnt(3)
	v_lshlrev_b32_e32 v2, 16, v208
	s_waitcnt lgkmcnt(0)
	v_mul_f32_e32 v2, v4, v2
	v_bfe_u32 v3, v2, 16, 1
	v_add3_u32 v2, v2, v3, s34
	ds_write_b16_d16_hi v185, v2 offset:1024
	v_and_b32_e32 v2, 0xffff0000, v208
	v_mul_f32_e32 v2, v4, v2
	v_bfe_u32 v3, v2, 16, 1
	v_add3_u32 v2, v2, v3, s34
	ds_write_b16_d16_hi v185, v2 offset:1168
	v_lshlrev_b32_e32 v2, 16, v209
	v_mul_f32_e32 v2, v4, v2
	v_bfe_u32 v3, v2, 16, 1
	v_add3_u32 v2, v2, v3, s34
	ds_write_b16_d16_hi v185, v2 offset:1312
	v_and_b32_e32 v2, 0xffff0000, v209
	v_mul_f32_e32 v2, v4, v2
	v_bfe_u32 v3, v2, 16, 1
	v_add3_u32 v2, v2, v3, s34
	ds_write_b16_d16_hi v185, v2 offset:1456
	v_lshlrev_b32_e32 v2, 16, v210
	v_mul_f32_e32 v2, v4, v2
	v_bfe_u32 v3, v2, 16, 1
	v_add3_u32 v2, v2, v3, s34
	ds_write_b16_d16_hi v185, v2 offset:1600
	v_and_b32_e32 v2, 0xffff0000, v210
	v_mul_f32_e32 v2, v4, v2
	v_bfe_u32 v3, v2, 16, 1
	v_add3_u32 v2, v2, v3, s34
	ds_write_b16_d16_hi v185, v2 offset:1744
	v_lshlrev_b32_e32 v2, 16, v211
	v_mul_f32_e32 v2, v4, v2
	v_bfe_u32 v3, v2, 16, 1
	v_add3_u32 v2, v2, v3, s34
	ds_write_b16_d16_hi v185, v2 offset:1888
	v_and_b32_e32 v2, 0xffff0000, v211
	v_mul_f32_e32 v2, v4, v2
	v_bfe_u32 v3, v2, 16, 1
	v_add3_u32 v2, v2, v3, s34
	ds_write_b16_d16_hi v185, v2 offset:2032
	s_waitcnt vmcnt(1)
	v_lshlrev_b32_e32 v2, 16, v212
	v_mul_f32_e32 v2, v4, v2
	v_bfe_u32 v3, v2, 16, 1
	v_add3_u32 v2, v2, v3, s34
	ds_write_b16_d16_hi v186, v2 offset:1024
	v_and_b32_e32 v2, 0xffff0000, v212
	v_mul_f32_e32 v2, v4, v2
	v_bfe_u32 v3, v2, 16, 1
	v_add3_u32 v2, v2, v3, s34
	ds_write_b16_d16_hi v186, v2 offset:1168
	v_lshlrev_b32_e32 v2, 16, v213
	v_mul_f32_e32 v2, v4, v2
	v_bfe_u32 v3, v2, 16, 1
	v_add3_u32 v2, v2, v3, s34
	ds_write_b16_d16_hi v186, v2 offset:1312
	v_and_b32_e32 v2, 0xffff0000, v213
	v_mul_f32_e32 v2, v4, v2
	v_bfe_u32 v3, v2, 16, 1
	v_add3_u32 v2, v2, v3, s34
	ds_write_b16_d16_hi v186, v2 offset:1456
	v_lshlrev_b32_e32 v2, 16, v214
	v_mul_f32_e32 v2, v4, v2
	v_bfe_u32 v3, v2, 16, 1
	v_add3_u32 v2, v2, v3, s34
	ds_write_b16_d16_hi v186, v2 offset:1600
	v_and_b32_e32 v2, 0xffff0000, v214
	v_mul_f32_e32 v2, v4, v2
	v_bfe_u32 v3, v2, 16, 1
	v_add3_u32 v2, v2, v3, s34
	ds_write_b16_d16_hi v186, v2 offset:1744
	v_lshlrev_b32_e32 v2, 16, v215
	v_mul_f32_e32 v2, v4, v2
	v_bfe_u32 v3, v2, 16, 1
	v_add3_u32 v2, v2, v3, s34
	ds_write_b16_d16_hi v186, v2 offset:1888
	v_and_b32_e32 v2, 0xffff0000, v215
	v_mul_f32_e32 v2, v4, v2
	v_bfe_u32 v3, v2, 16, 1
	v_add3_u32 v2, v2, v3, s34
	ds_write_b16_d16_hi v186, v2 offset:2032
	s_waitcnt vmcnt(0)
	v_lshlrev_b32_e32 v2, 16, v216
	v_mul_f32_e32 v2, v4, v2
	v_bfe_u32 v3, v2, 16, 1
	v_add3_u32 v2, v2, v3, s34
	ds_write_b16_d16_hi v187, v2 offset:1024
	v_and_b32_e32 v2, 0xffff0000, v216
	v_mul_f32_e32 v2, v4, v2
	v_bfe_u32 v3, v2, 16, 1
	v_add3_u32 v2, v2, v3, s34
	ds_write_b16_d16_hi v187, v2 offset:1168
	v_lshlrev_b32_e32 v2, 16, v217
	v_mul_f32_e32 v2, v4, v2
	v_bfe_u32 v3, v2, 16, 1
	v_add3_u32 v2, v2, v3, s34
	ds_write_b16_d16_hi v187, v2 offset:1312
	v_and_b32_e32 v2, 0xffff0000, v217
	v_mul_f32_e32 v2, v4, v2
	v_bfe_u32 v3, v2, 16, 1
	v_add3_u32 v2, v2, v3, s34
	ds_write_b16_d16_hi v187, v2 offset:1456
	v_lshlrev_b32_e32 v2, 16, v218
	v_mul_f32_e32 v2, v4, v2
	v_bfe_u32 v3, v2, 16, 1
	v_add3_u32 v2, v2, v3, s34
	ds_write_b16_d16_hi v187, v2 offset:1600
	v_and_b32_e32 v2, 0xffff0000, v218
	v_mul_f32_e32 v2, v4, v2
	v_bfe_u32 v3, v2, 16, 1
	v_add3_u32 v2, v2, v3, s34
	ds_write_b16_d16_hi v187, v2 offset:1744
	v_lshlrev_b32_e32 v2, 16, v219
	v_mul_f32_e32 v2, v4, v2
	v_bfe_u32 v3, v2, 16, 1
	v_add3_u32 v2, v2, v3, s34
	ds_write_b16_d16_hi v187, v2 offset:1888
	v_and_b32_e32 v2, 0xffff0000, v219
	v_mul_f32_e32 v2, v4, v2
	v_bfe_u32 v3, v2, 16, 1
	v_add3_u32 v2, v2, v3, s34
	ds_write_b16_d16_hi v187, v2 offset:2032
	v_lshlrev_b32_e32 v5, 16, v220
	v_mul_f32_e32 v5, v4, v5
	v_bfe_u32 v6, v5, 16, 1
	v_and_b32_e32 v0, 0xffff0000, v220
	v_add3_u32 v5, v5, v6, s34
	v_mul_f32_e32 v0, v4, v0
	ds_write_b16_d16_hi v188, v5 offset:1024
	v_bfe_u32 v5, v0, 16, 1
	v_add3_u32 v0, v0, v5, s34
	ds_write_b16_d16_hi v188, v0 offset:1168
	v_lshlrev_b32_e32 v0, 16, v221
	v_mul_f32_e32 v0, v4, v0
	v_bfe_u32 v5, v0, 16, 1
	v_add3_u32 v0, v0, v5, s34
	ds_write_b16_d16_hi v188, v0 offset:1312
	v_and_b32_e32 v0, 0xffff0000, v221
	v_mul_f32_e32 v0, v4, v0
	v_bfe_u32 v1, v0, 16, 1
	v_add3_u32 v0, v0, v1, s34
	ds_write_b16_d16_hi v188, v0 offset:1456
	v_lshlrev_b32_e32 v0, 16, v222
	v_mul_f32_e32 v0, v4, v0
	v_bfe_u32 v1, v0, 16, 1
	v_add3_u32 v0, v0, v1, s34
	ds_write_b16_d16_hi v188, v0 offset:1600
	v_and_b32_e32 v0, 0xffff0000, v222
	v_mul_f32_e32 v0, v4, v0
	v_bfe_u32 v1, v0, 16, 1
	v_add3_u32 v0, v0, v1, s34
	ds_write_b16_d16_hi v188, v0 offset:1744
	v_lshlrev_b32_e32 v0, 16, v223
	v_mul_f32_e32 v0, v4, v0
	v_bfe_u32 v1, v0, 16, 1
	v_add3_u32 v0, v0, v1, s34
	ds_write_b16_d16_hi v188, v0 offset:1888
	v_and_b32_e32 v0, 0xffff0000, v223
	v_mul_f32_e32 v0, v4, v0
	v_bfe_u32 v1, v0, 16, 1
	v_add3_u32 v0, v0, v1, s34
	ds_write_b16_d16_hi v188, v0 offset:2032
	s_waitcnt lgkmcnt(0)
	s_barrier
; #define LAS __attribute__((address_space(3)))
; __device__ __forceinline__ float bflo(unsigned w) { return __uint_as_float(w << 16); }
; __device__ __forceinline__ float bfhi(unsigned w) { return __uint_as_float(w & 0xffff0000u); }
; __device__ __forceinline__ void mlstm_stage_a(LAS unsigned char* lds, const bf16_t* QKO, const bf16_t* KVT, const float* G, const float* gbias, bf16_t* DC, float* DN, float* SC,
;                                               int bid, int nblk, int tid) {
;     ...
;         if (tid < 256) { float s = 0.f;
; #pragma unroll
;             for (int j = 0; j < 8; ++j) { const u32x4 w = *(const LAS u32x4*)(sKS + tid * 144 + j * 16);
;                 s += (bflo(w.x) + bfhi(w.x)) + (bflo(w.y) + bfhi(w.y)) + (bflo(w.z) + bfhi(w.z)) + (bflo(w.w) + bfhi(w.w)); }
;             DN[(size_t)(c * 4 + h) * 256 + tid] = s; }
	s_and_saveexec_b64 s[24:25], s[18:19]
	s_cbranch_execz .LBB0_535
	ds_read_b128 v[0:3], v189 offset:1024
	ds_read_b128 v[4:7], v189 offset:1040
	ds_read_b128 v[8:11], v189 offset:1056
	ds_read_b128 v[12:15], v189 offset:1072
	s_waitcnt lgkmcnt(3)
	v_lshlrev_b32_e32 v16, 16, v0
	s_waitcnt lgkmcnt(2)
	v_lshlrev_b32_e32 v17, 16, v4
	v_and_b32_e32 v19, 0xffff0000, v4
	v_and_b32_e32 v18, 0xffff0000, v0
	v_pk_add_f32 v[16:17], v[16:17], v[18:19]
	v_lshlrev_b32_e32 v19, 16, v5
	v_lshlrev_b32_e32 v18, 16, v1
	v_and_b32_e32 v5, 0xffff0000, v5
	v_and_b32_e32 v4, 0xffff0000, v1
	v_pk_add_f32 v[0:1], v[18:19], v[4:5]
	v_lshlrev_b32_e32 v5, 16, v6
	v_pk_add_f32 v[0:1], v[16:17], v[0:1]
	v_lshlrev_b32_e32 v4, 16, v2
	v_and_b32_e32 v17, 0xffff0000, v6
	v_and_b32_e32 v16, 0xffff0000, v2
	v_pk_add_f32 v[4:5], v[4:5], v[16:17]
	v_and_b32_e32 v6, 0xffff0000, v3
	v_pk_add_f32 v[0:1], v[4:5], v[0:1]
	v_lshlrev_b32_e32 v5, 16, v7
	v_lshlrev_b32_e32 v4, 16, v3
	v_and_b32_e32 v7, 0xffff0000, v7
	v_pk_add_f32 v[2:3], v[4:5], v[6:7]
	s_waitcnt lgkmcnt(1)
	v_and_b32_e32 v7, 0xffff0000, v11
	v_pk_add_f32 v[0:1], v[2:3], v[0:1]
	v_and_b32_e32 v3, 0xffff0000, v9
	v_add_f32_e32 v0, 0, v0
	v_add_f32_e32 v4, v0, v1
	v_lshlrev_b32_e32 v1, 16, v9
	v_lshlrev_b32_e32 v0, 16, v8
	v_and_b32_e32 v2, 0xffff0000, v8
	v_pk_add_f32 v[0:1], v[0:1], v[2:3]
	v_lshlrev_b32_e32 v3, 16, v11
	v_lshlrev_b32_e32 v2, 16, v10
	v_and_b32_e32 v6, 0xffff0000, v10
	v_pk_add_f32 v[0:1], v[0:1], v[0:1] op_sel:[0,1] op_sel_hi:[1,0]
	v_pk_add_f32 v[6:7], v[2:3], v[6:7]
	s_waitcnt lgkmcnt(0)
	v_lshlrev_b32_e32 v16, 16, v14
	v_pk_add_f32 v[8:9], v[6:7], v[0:1]
	v_lshlrev_b32_e32 v0, 16, v12
	v_and_b32_e32 v1, 0xffff0000, v12
	v_add_f32_e32 v10, v0, v1
	v_lshlrev_b32_e32 v0, 16, v13
	v_and_b32_e32 v1, 0xffff0000, v13
	v_add_f32_e32 v12, v0, v1
	ds_read_b128 v[0:3], v189 offset:1088
	s_waitcnt lgkmcnt(0)
	v_lshlrev_b32_e32 v11, 16, v1
	v_and_b32_e32 v13, 0xffff0000, v1
	v_lshlrev_b32_e32 v17, 16, v0
	v_and_b32_e32 v1, 0xffff0000, v0
	v_and_b32_e32 v0, 0xffff0000, v14
	v_pk_add_f32 v[0:1], v[16:17], v[0:1]
	v_pk_add_f32 v[10:11], v[10:11], v[12:13]
	v_lshlrev_b32_e32 v5, 16, v3
	v_pk_add_f32 v[0:1], v[0:1], v[10:11]
	v_pk_mov_b32 v[10:11], v[14:15], v[2:3] op_sel:[1,0]
	v_and_b32_e32 v18, 0xffff0000, v3
	v_lshlrev_b32_e32 v3, 16, v2
	v_lshlrev_b32_e32 v2, 16, v15
	v_and_b32_e32 v11, 0xffff0000, v11
	v_and_b32_e32 v10, 0xffff0000, v10
	v_pk_add_f32 v[2:3], v[2:3], v[10:11]
	s_nop 0
	v_pk_add_f32 v[0:1], v[2:3], v[0:1]
	v_pk_add_f32 v[2:3], v[6:7], v[8:9] op_sel:[1,0] op_sel_hi:[0,1]
	v_mov_b32_e32 v3, v18
	v_pk_add_f32 v[2:3], v[4:5], v[2:3]
	s_nop 0
	v_pk_add_f32 v[0:1], v[2:3], v[0:1]
	ds_read_b128 v[2:5], v189 offset:1104
	v_pk_add_f32 v[0:1], v[0:1], v[0:1] op_sel:[0,1] op_sel_hi:[1,0]
	s_waitcnt lgkmcnt(0)
	v_lshlrev_b32_e32 v7, 16, v3
	v_lshlrev_b32_e32 v6, 16, v2
	v_and_b32_e32 v3, 0xffff0000, v3
	v_and_b32_e32 v2, 0xffff0000, v2
	v_pk_add_f32 v[2:3], v[6:7], v[2:3]
	v_lshlrev_b32_e32 v7, 16, v5
	v_lshlrev_b32_e32 v6, 16, v4
	v_and_b32_e32 v5, 0xffff0000, v5
	v_and_b32_e32 v4, 0xffff0000, v4
	v_pk_add_f32 v[2:3], v[2:3], v[2:3] op_sel:[0,1] op_sel_hi:[1,0]
	v_pk_add_f32 v[10:11], v[6:7], v[4:5]
	s_nop 0
	v_pk_add_f32 v[12:13], v[10:11], v[2:3]
	ds_read_b128 v[2:5], v189 offset:1120
	s_waitcnt lgkmcnt(0)
	v_lshlrev_b32_e32 v6, 16, v2
	v_and_b32_e32 v2, 0xffff0000, v2
	v_add_f32_e32 v2, v6, v2
	v_lshlrev_b32_e32 v6, 16, v3
	v_and_b32_e32 v3, 0xffff0000, v3
	v_add_f32_e32 v14, v6, v3
	ds_read_b128 v[6:9], v189 offset:1136
	v_lshlrev_b32_e32 v16, 16, v4
	s_waitcnt lgkmcnt(0)
	v_lshlrev_b32_e32 v3, 16, v7
	v_and_b32_e32 v15, 0xffff0000, v7
	v_lshlrev_b32_e32 v17, 16, v6
	v_and_b32_e32 v7, 0xffff0000, v6
	v_and_b32_e32 v6, 0xffff0000, v4
	v_pk_add_f32 v[6:7], v[16:17], v[6:7]
	v_pk_add_f32 v[2:3], v[2:3], v[14:15]
	v_lshlrev_b32_e32 v18, 16, v9
	v_pk_add_f32 v[2:3], v[6:7], v[2:3]
	v_pk_mov_b32 v[6:7], v[4:5], v[8:9] op_sel:[1,0]
	v_and_b32_e32 v19, 0xffff0000, v9
	v_lshlrev_b32_e32 v9, 16, v8
	v_lshlrev_b32_e32 v8, 16, v5
	v_and_b32_e32 v5, 0xffff0000, v7
	v_and_b32_e32 v4, 0xffff0000, v6
	v_pk_add_f32 v[4:5], v[8:9], v[4:5]
	v_mov_b32_e32 v1, v18
	v_pk_add_f32 v[2:3], v[4:5], v[2:3]
	v_pk_add_f32 v[4:5], v[10:11], v[12:13] op_sel:[1,0] op_sel_hi:[0,1]
	v_mov_b32_e32 v5, v19
	v_pk_add_f32 v[0:1], v[0:1], v[4:5]
	s_nop 0
	v_pk_add_f32 v[0:1], v[0:1], v[2:3]
	s_nop 0
	v_add_f32_e32 v0, v0, v1
	global_store_dword v[174:175], v0, off
	s_branch .LBB0_535
